# gate: a block's four units share one (b,h); centroid table built once per block (largest cb first) and reused
# baseline (speedup 1.0000x reference)
.LBB0_1086:
	s_cmp_eq_u32 s58, 0x200
	s_cbranch_scc1 .Lg_map512
	s_mov_b32 s64, s11
	s_mov_b32 s65, 1
	s_branch .Lg_mapdone
.Lg_map512:
	s_and_b32 s65, s11, 7
	s_sub_i32 s15, 15, s65
	s_bitcmp1_b32 s11, 9
	s_cselect_b32 s65, s65, s15
	s_bitcmp0_b32 s11, 10
	s_cselect_b32 s15, 16, 0
	s_add_i32 s65, s65, s15
	s_bfe_u32 s64, s11, 0x60003
	s_lshl_b32 s64, s64, 5
	s_or_b32 s64, s64, s65
	s_lshr_b32 s65, s11, 9
	s_cmp_eq_u32 s65, 0
	s_cselect_b32 s65, 1, 0
.Lg_mapdone:
	s_and_b32 s15, s64, 31
	s_lshl_b32 s33, s15, 6
	s_mul_i32 s33, s33, s65
	s_and_b32 s14, s64, 31
	v_cmp_gt_i32_e32 vcc, s33, v0
	s_barrier
	s_and_saveexec_b64 s[2:3], vcc
	s_cbranch_execz .LBB0_1101
	s_lshl_b32 s4, s14, 6
	v_max_i32_e32 v4, s4, v1
	v_add_u32_e32 v6, v4, v70
	s_and_b32 s35, s64, 0xffffffe0
	v_cmp_lt_u32_e32 vcc, s1, v6
	s_mov_b64 s[16:17], -1
	v_mov_b32_e32 v4, v0
	v_mov_b32_e32 v5, v71
	s_and_saveexec_b64 s[4:5], vcc
	s_cbranch_execz .LBB0_1098
	v_lshrrev_b32_e32 v6, 8, v6
	v_add_u32_e32 v4, -1, v6
	v_lshrrev_b32_e32 v7, 1, v4
	v_cmp_lt_u32_e32 vcc, 5, v4
	v_mov_b32_e32 v11, 0
	v_add_u32_e32 v8, 1, v7
	v_mov_b64_e32 v[4:5], v[0:1]
	s_and_saveexec_b64 s[16:17], vcc
	s_cbranch_execz .LBB0_1092
	v_and_b32_e32 v9, -4, v8
	s_mov_b32 s38, 0
	s_mov_b64 s[36:37], 0
	v_mov_b32_e32 v10, v72
	v_mov_b64_e32 v[4:5], v[0:1]
